# attention prologue: the wait for the LDS-image fill loads moved after the first item's K/V loads are issued
# baseline (speedup 1.0000x reference)
.LBB0_337:
	s_cmp_lt_i32 s86, 3
	s_cselect_b64 s[0:1], -1, 0
	s_and_b64 s[88:89], s[0:1], s[6:7]
	s_waitcnt lgkmcnt(1)
	v_cndmask_b32_e64 v0, 0, 1, s[88:89]
	v_cmp_ne_u32_e64 s[68:69], 1, v0
	s_andn2_b64 vcc, exec, s[88:89]
	s_cbranch_vccnz .LBB0_410
	v_writelane_b32 v255, s88, 10
	s_cmpk_gt_i32 s97, 0x3ff
	v_readfirstlane_b32 s0, v251
	v_writelane_b32 v255, s89, 11
	v_writelane_b32 v255, s68, 12
	s_nop 1
	v_writelane_b32 v255, s69, 13
	s_cbranch_scc1 .LBB0_359
	s_lshl_b32 s56, s97, 12
	s_and_b32 s56, s56, 0x3c000
	s_add_u32 s58, s84, 0x80000
	s_addc_u32 s59, s85, 0
	s_add_u32 s58, s58, s56
	s_addc_u32 s59, s59, 0
	s_add_u32 s88, s58, 0x40000
	s_addc_u32 s89, s59, 0
	v_lshlrev_b32_e32 v14, 4, v251
	v_add_u32_e32 v15, 0x2000, v14
	global_load_dwordx4 v[16:19], v14, s[58:59]
	global_load_dwordx4 v[20:23], v15, s[58:59]
	global_load_dwordx4 v[24:27], v14, s[88:89]
	global_load_dwordx4 v[28:31], v15, s[88:89]
	s_and_b32 s56, s97, 3
	s_lshl_b32 s56, s56, 2
	v_lshrrev_b32_e32 v32, 1, v254
	v_add_lshl_u32 v32, v32, s56, 2
	global_load_dword v253, v32, s[80:81]
	v_bfe_u32 v33, v251, 2, 1
	v_and_b32_e32 v34, 1, v251
	v_lshlrev_b32_e32 v33, 2, v33
	v_lshl_or_b32 v33, v34, 1, v33
	v_bfe_u32 v34, v251, 8, 1
	v_or_b32_e32 v33, v33, v34
	v_cmp_ne_u32_e32 vcc, 0, v33
	v_mov_b32_e32 v35, 0x680
	v_cndmask_b32_e32 v35, 0, v35, vcc
	v_lshlrev_b32_e32 v33, 11, v33
	v_bfe_u32 v34, v251, 1, 1
	v_lshl_add_u32 v33, v34, 9, v33
	v_bfe_u32 v34, v251, 3, 5
	v_lshl_add_u32 v33, v34, 4, v33
	v_add_u32_e32 v33, 0x1b200, v33
	v_add_u32_e32 v35, v35, v33
	v_add_u32_e32 v35, 0x4000, v35
	v_and_b32_e32 v252, 0x7f, v251
	v_lshlrev_b32_e32 v252, 4, v252
	v_add_u32_e32 v252, 0x1b200, v252
	v_and_b32_e32 v250, 63, v251
	v_and_b32_e32 v248, 7, v250
	v_lshlrev_b32_e32 v248, 4, v248
	v_mov_b32_e32 v249, 0
	v_lshrrev_b32_e32 v250, 3, v250
	v_lshl_add_u32 v250, v254, 5, v250
	v_and_b32_e32 v10, 63, v251
	v_lshlrev_b32_e32 v10, 2, v10
	global_load_dword v11, v10, s[78:79]
	global_load_dword v12, v10, s[76:77]
	v_mov_b32_e32 v13, 0
	v_add_u32_e32 v13, 0x1b000, v13
	v_add_u32_e32 v10, v13, v10
	s_lshl_b32 s96, s97, 5
	s_and_b32 s7, s96, 0x780
	v_mov_b32_e32 v80, 0
	v_lshrrev_b32_e32 v182, 1, v251
	s_addk_i32 s7, 0xff80
	v_mov_b32_e32 v82, v80
	v_mov_b32_e32 v83, v80
	v_add_u32_e32 v0, s7, v182
	v_mov_b32_e32 v81, v80
	v_mov_b64_e32 v[86:87], v[82:83]
	v_mov_b64_e32 v[94:95], v[82:83]
	v_mov_b64_e32 v[90:91], v[82:83]
	s_ashr_i32 s6, s97, 6
	s_and_b32 s1, s97, 3
	v_cmp_lt_i32_e32 vcc, -1, v0
	s_mov_b32 s5, 0
	v_mov_b64_e32 v[84:85], v[80:81]
	v_mov_b64_e32 v[92:93], v[80:81]
	v_mov_b64_e32 v[88:89], v[80:81]
	s_and_saveexec_b64 s[2:3], vcc
	s_cbranch_execz .LBB0_341
	v_readlane_b32 s8, v255, 6
	v_readlane_b32 s9, v255, 7
	v_add_u32_e32 v2, s7, v250
	v_lshl_add_u32 v2, s6, 11, v2
	s_movk_i32 s4, 0xc00
	v_mov_b64_e32 v[0:1], s[8:9]
	v_mad_i64_i32 v[0:1], s[8:9], v2, s4, v[0:1]
	s_lshl_b32 s4, s1, 7
	v_lshl_add_u64 v[0:1], v[0:1], 0, s[4:5]
	v_lshl_add_u64 v[0:1], v[0:1], 0, v[248:249]
	s_movk_i32 s4, 0x6000
	global_load_dwordx4 v[80:83], v[0:1], off offset:2048
	v_lshl_add_u64 v[0:1], v[0:1], 0, s[4:5]
	global_load_dwordx4 v[84:87], v[0:1], off offset:2048
	v_lshl_add_u64 v[0:1], v[0:1], 0, s[4:5]
	global_load_dwordx4 v[88:91], v[0:1], off offset:2048
	v_lshl_add_u64 v[0:1], v[0:1], 0, s[4:5]
	global_load_dwordx4 v[92:95], v[0:1], off offset:2048

.LBB0_345:
	s_or_b64 exec, exec, s[2:3]
	s_waitcnt vmcnt(0)
	ds_write_b128 v33, v[16:19]
	ds_write_b128 v33, v[20:23] offset:1024
	ds_write_b128 v35, v[24:27]
	ds_write_b128 v35, v[28:31] offset:1024
	ds_write_b32 v10, v11
	ds_write_b32 v10, v12 offset:256
	s_waitcnt lgkmcnt(0)
	v_mbcnt_lo_u32_b32 v0, -1, 0
	v_mbcnt_hi_u32_b32 v4, -1, v0
	v_and_b32_e32 v1, 64, v4
	v_xor_b32_e32 v0, 1, v4
	v_add_u32_e32 v5, 64, v1
	v_bfe_u32 v3, v251, 5, 1
	v_cmp_lt_i32_e32 vcc, v0, v5
	v_xor_b32_e32 v10, 32, v4
	v_and_b32_e32 v184, 31, v251
	v_cndmask_b32_e32 v0, v4, v0, vcc
	v_cmp_lt_i32_e32 vcc, v10, v5
	v_lshlrev_b32_e32 v5, 2, v3
	v_or_b32_e32 v16, 2, v5
	v_cmp_gt_u32_e64 s[6:7], v16, v184
	v_or_b32_e32 v16, 3, v5
	s_add_u32 s82, s84, 0x80000
	v_cmp_gt_u32_e64 s[8:9], v16, v184
	v_or_b32_e32 v16, 8, v5
	s_addc_u32 s83, s85, 0
	v_cmp_gt_u32_e64 s[10:11], v16, v184
	v_or_b32_e32 v16, 9, v5
	s_add_u32 s92, s84, 0xc0000
	v_cmp_gt_u32_e64 s[12:13], v16, v184
	v_or_b32_e32 v16, 10, v5
	s_addc_u32 s93, s85, 0
	s_lshr_b32 s1, s0, 7
	s_and_b32 s91, s0, 64
	s_movk_i32 s0, 0x90
	v_cmp_gt_u32_e64 s[14:15], v16, v184
	v_or_b32_e32 v16, 11, v5
	v_mad_u32_u24 v6, v182, s0, 0
	s_movk_i32 s0, 0x208
	v_cmp_gt_u32_e64 s[16:17], v16, v184
	v_or_b32_e32 v16, 16, v5
	v_lshlrev_b32_e32 v96, 4, v3
	v_mad_u32_u24 v9, v120, s0, 0
	v_cndmask_b32_e32 v4, v4, v10, vcc
	s_lshr_b32 s0, s91, 5
	v_cmp_gt_u32_e64 s[18:19], v16, v184
	v_or_b32_e32 v16, 17, v5
	v_writelane_b32 v255, s1, 14
	v_lshlrev_b32_e32 v126, 3, v3
	v_lshlrev_b32_e32 v188, 2, v4
	v_add_u32_e32 v4, 0, v96
	s_or_b32 s1, s0, 1
	s_add_i32 s33, s0, 2
	s_add_i32 s54, s0, 3
	s_or_b32 s0, s0, 4
	v_cmp_gt_u32_e64 s[20:21], v16, v184
	v_or_b32_e32 v16, 18, v5
	v_sub_u32_e32 v10, v4, v126
	v_cmp_gt_u32_e64 s[22:23], v16, v184
	v_or_b32_e32 v16, 19, v5
	s_cmp_eq_u32 s91, 0
	v_readlane_b32 s2, v255, 6
	v_lshl_or_b32 v15, s0, 5, v184
	v_cmp_gt_u32_e64 s[24:25], v16, v184
	v_or_b32_e32 v16, 24, v5
	s_cselect_b64 s[36:37], -1, 0
	v_lshl_add_u32 v20, s0, 6, v10
	s_or_b32 s0, s91, 32
	v_mov_b32_e32 v127, v97
	v_readlane_b32 s3, v255, 7
	v_lshl_or_b32 v12, s1, 5, v184
	v_cmp_gt_u32_e64 s[26:27], v16, v184
	v_or_b32_e32 v16, 25, v5
	v_lshl_add_u32 v17, s1, 6, v10
	s_lshr_b32 s1, s0, 5
	v_lshl_add_u64 v[146:147], s[2:3], 0, v[126:127]
	v_lshl_or_b32 v13, s33, 5, v184
	v_lshl_or_b32 v14, s54, 5, v184
	v_cmp_gt_u32_e64 s[2:3], v5, v184
	v_cmp_lt_u32_e64 s[4:5], v5, v184
	v_cmp_gt_u32_e64 s[28:29], v16, v184
	v_or_b32_e32 v16, 26, v5
	v_or_b32_e32 v5, 27, v5
	v_lshl_add_u32 v18, s33, 6, v10
	v_lshl_add_u32 v19, s54, 6, v10
	s_add_i32 s33, s1, 1
	s_add_i32 s54, s1, 2
	s_add_i32 s55, s1, 3
	s_or_b32 s1, s1, 4
	v_writelane_b32 v255, s0, 15
	v_and_b32_e32 v2, 1, v251
	v_cmp_gt_u32_e64 s[34:35], v5, v184
	v_lshl_add_u32 v5, s91, 1, v10
	v_or_b32_e32 v21, s0, v184
	v_lshl_or_b32 v25, s1, 5, v184
	v_lshl_add_u32 v26, s0, 1, v10
	v_lshl_add_u32 v27, s33, 6, v10
	v_lshl_add_u32 v28, s54, 6, v10
	v_lshl_add_u32 v29, s55, 6, v10
	v_lshl_add_u32 v10, s1, 6, v10
	v_readlane_b32 s0, v255, 1
	v_or_b32_e32 v185, s91, v184
	v_lshlrev_b32_e32 v187, 2, v0
	v_lshlrev_b32_e32 v0, 6, v2
	v_lshlrev_b32_e32 v7, 5, v2
	v_lshlrev_b32_e32 v2, 4, v251
	v_lshl_or_b32 v22, s33, 5, v184
	v_lshl_or_b32 v23, s54, 5, v184
	v_lshl_or_b32 v24, s55, 5, v184
	v_readlane_b32 s1, v255, 2
	v_mov_b32_e32 v1, v97
	v_and_b32_e32 v8, 0x3fc, v251
	v_and_b32_e32 v2, 16, v2
	v_mul_u32_u24_e32 v11, 0x90, v185
	v_mul_u32_u24_e32 v12, 0x90, v12
	v_mul_u32_u24_e32 v13, 0x90, v13
	v_mul_u32_u24_e32 v14, 0x90, v14
	v_mul_u32_u24_e32 v15, 0x90, v15
	v_cmp_gt_u32_e64 s[30:31], v16, v184
	v_mul_u32_u24_e32 v16, 0x208, v184
	v_mul_u32_u24_e32 v21, 0x90, v21
	v_mul_u32_u24_e32 v22, 0x90, v22
	v_mul_u32_u24_e32 v23, 0x90, v23
	v_mul_u32_u24_e32 v24, 0x90, v24
	v_mul_u32_u24_e32 v25, 0x90, v25
	v_lshlrev_b32_e32 v96, 5, v3
	s_lshl_b32 s1, s0, 5
	s_lshl_b32 s0, s0, 2
	v_add_u32_e32 v186, 0xffffff80, v182
	s_mov_b32 s95, 0
	v_lshl_add_u64 v[142:143], s[82:83], 0, v[0:1]
	v_lshl_add_u64 v[144:145], s[92:93], 0, v[0:1]
	v_or_b32_e32 v127, 16, v126
	v_lshl_add_u64 v[148:149], s[78:79], 0, v[0:1]
	v_lshl_add_u64 v[150:151], s[76:77], 0, v[96:97]
	v_mov_b32_e32 v242, 0
	v_add_u32_e32 v242, 0x1b000, v242
	v_add_u32_e32 v243, v242, v96
	v_add_u32_e32 v243, 0x100, v243
	v_add_u32_e32 v242, v242, v0
	s_lshl_b32 s90, s97, 2
	v_writelane_b32 v255, s0, 16
	s_movk_i32 s65, 0xc00
	s_mov_b32 s54, 0xffff0000
	v_mov_b32_e32 v189, 0x358637bd
	v_add_u32_e32 v190, v6, v7
	v_add_u32_e32 v191, v9, v8
	v_lshlrev_b32_e32 v152, 1, v2
	v_add_u32_e32 v192, v4, v11
	v_add_u32_e32 v193, v4, v12
	v_add_u32_e32 v194, v4, v13
	v_add_u32_e32 v195, v4, v14
	v_add_u32_e32 v196, v4, v15
	v_add_u32_e32 v197, v5, v16
	v_add_u32_e32 v198, v17, v16
	v_add_u32_e32 v199, v18, v16
	v_add_u32_e32 v200, v19, v16
	v_add_u32_e32 v201, v20, v16
	v_add_u32_e32 v202, v4, v21
	v_add_u32_e32 v203, v4, v22
	v_add_u32_e32 v204, v4, v23
	v_add_u32_e32 v205, v4, v24
	v_add_u32_e32 v206, v4, v25
	v_add_u32_e32 v207, v26, v16
	v_add_u32_e32 v208, v27, v16
	v_add_u32_e32 v209, v28, v16
	v_add_u32_e32 v210, v29, v16
	v_add_u32_e32 v211, v10, v16
	v_mov_b32_e32 v212, 0xff800000
	s_mov_b32 s33, s97
	s_branch .LBB0_348
